# L1-P3 short-conv: next tile's 30 operand loads requested before the current tile's transpose/stores
# baseline (speedup 1.0000x reference)
.LBB0_1292:
	s_or_b64 exec, exec, s[6:7]
	s_waitcnt lgkmcnt(0)
	v_mov_b32_e32 v0, v254
	v_mov_b64_e32 v[2:3], s[40:41]
	s_barrier
	flat_load_dwordx2 v[4:5], v[2:3] offset:248 sc0 sc1
	flat_load_dwordx2 v[6:7], v[2:3] offset:256 sc0 sc1
	s_waitcnt vmcnt(0)
	s_add_u32 s46, s26, 0xd200000
	s_addc_u32 s47, s27, 0
	s_add_u32 s54, s26, 0x9200000
	s_addc_u32 s55, s27, 0
	s_cmpk_lt_i32 s2, 0x1000
	s_waitcnt lgkmcnt(0)
	v_readfirstlane_b32 s9, v5
	v_readfirstlane_b32 s8, v4
	v_readfirstlane_b32 s11, v7
	v_readfirstlane_b32 s10, v6
	s_cbranch_scc0 .LBB0_1319
	v_ashrrev_i32_e32 v5, 4, v0
	v_lshlrev_b32_e32 v1, 2, v0
	v_ashrrev_i32_e32 v55, 3, v0
	v_lshlrev_b32_e32 v0, 3, v0
	s_add_u32 s12, s8, 0x6000
	v_and_b32_e32 v4, 56, v0
	s_movk_i32 s4, 0x41
	v_and_b32_e32 v54, 60, v1
	s_addc_u32 s13, s9, 0
	v_mad_u64_u32 v[0:1], s[0:1], v55, s4, v[4:5]
	s_add_u32 s14, s8, 0xc000
	v_lshl_add_u32 v56, v0, 2, 0
	v_mad_u32_u24 v0, v54, s4, v5
	s_addc_u32 s15, s9, 0
	v_mov_b32_e32 v7, 0
	v_or_b32_e32 v57, 0x800, v54
	v_or_b32_e32 v58, 0x1000, v54
	v_lshl_add_u32 v59, v0, 2, 0
	s_lshl_b32 s4, s2, 1
	s_lshl_b32 s5, s30, 1
	s_lshl_b32 s18, s2, 6
	s_lshl_b32 s19, s30, 6
	s_movk_i32 s20, 0x3000
	v_mov_b64_e32 v[8:9], s[48:49]
	s_movk_i32 s21, 0x1fff
	s_mov_b32 s23, 0xd200000
	s_mov_b32 s24, s2
	s_and_b32 s0, s4, 0xffffffc0
	s_and_b32 s1, s18, 0x7c0
	v_add_u32_e32 v174, s0, v5
	v_or_b32_e32 v175, s1, v54
	v_lshlrev_b32_e32 v176, 1, v175
	v_lshlrev_b32_e32 v177, 2, v175
	v_mul_u32_u24_e32 v154, 0x3000, v174
	v_max_i32_e32 v155, 1, v174
	v_add_u32_e32 v154, v154, v176
	v_add_u32_e32 v155, -1, v155
	v_mul_u32_u24_e32 v155, 0x3000, v155
	v_add_u32_e32 v155, v155, v176
	global_load_dwordx2 v[70:71], v155, s[48:49]
	v_add_u32_e32 v156, 0x1000, v155
	global_load_dwordx2 v[72:73], v156, s[48:49]
	v_add_u32_e32 v157, 0x2000, v155
	global_load_dwordx2 v[74:75], v157, s[48:49]
	global_load_dwordx2 v[76:77], v154, s[48:49]
	v_add_u32_e32 v158, 0x1000, v154
	global_load_dwordx2 v[78:79], v158, s[48:49]
	v_add_u32_e32 v159, 0x2000, v154
	global_load_dwordx2 v[80:81], v159, s[48:49]
	v_add_u32_e32 v160, 0x3000, v154
	global_load_dwordx2 v[82:83], v160, s[48:49]
	v_add_u32_e32 v161, 0x4000, v154
	global_load_dwordx2 v[84:85], v161, s[48:49]
	v_add_u32_e32 v162, 0x5000, v154
	global_load_dwordx2 v[86:87], v162, s[48:49]
	v_add_u32_e32 v163, 0x5d000, v154
	global_load_dwordx2 v[88:89], v163, s[48:49]
	v_add_u32_e32 v164, 0x5e000, v154
	global_load_dwordx2 v[90:91], v164, s[48:49]
	v_add_u32_e32 v165, 0x5f000, v154
	global_load_dwordx2 v[92:93], v165, s[48:49]
	v_add_u32_e32 v166, 0x60000, v154
	global_load_dwordx2 v[94:95], v166, s[48:49]
	v_add_u32_e32 v167, 0x61000, v154
	global_load_dwordx2 v[96:97], v167, s[48:49]
	v_add_u32_e32 v168, 0x62000, v154
	global_load_dwordx2 v[98:99], v168, s[48:49]
	v_add_u32_e32 v169, 0x63000, v154
	global_load_dwordx2 v[100:101], v169, s[48:49]
	v_add_u32_e32 v170, 0x64000, v154
	global_load_dwordx2 v[102:103], v170, s[48:49]
	v_add_u32_e32 v171, 0x65000, v154
	global_load_dwordx2 v[104:105], v171, s[48:49]
	v_add_u32_e32 v172, 0x2000, v177
	v_add_u32_e32 v173, 0x4000, v177
	global_load_dwordx4 v[118:121], v177, s[12:13]
	global_load_dwordx4 v[122:125], v172, s[12:13]
	global_load_dwordx4 v[126:129], v173, s[12:13]
	global_load_dwordx4 v[142:145], v177, s[10:11]
	global_load_dwordx4 v[146:149], v172, s[10:11]
	global_load_dwordx4 v[150:153], v173, s[10:11]
	global_load_dwordx4 v[130:133], v177, s[14:15]
	global_load_dwordx4 v[134:137], v172, s[14:15]
	global_load_dwordx4 v[138:141], v173, s[14:15]
	global_load_dwordx4 v[106:109], v177, s[8:9]
	global_load_dwordx4 v[110:113], v172, s[8:9]
	global_load_dwordx4 v[114:117], v173, s[8:9]
	s_branch .LBB0_1295
.LBB0_1294:
	s_or_b64 exec, exec, s[0:1]
	s_add_i32 s0, s4, s5
	s_and_b32 s0, s0, 0xffffffc0
	s_add_i32 s1, s18, s19
	s_and_b32 s1, s1, 0x7c0
	v_add_u32_e32 v174, s0, v5
	v_or_b32_e32 v175, s1, v54
	v_lshlrev_b32_e32 v176, 1, v175
	v_lshlrev_b32_e32 v177, 2, v175
	v_mul_u32_u24_e32 v154, 0x3000, v174
	v_max_i32_e32 v155, 1, v174
	v_add_u32_e32 v154, v154, v176
	v_add_u32_e32 v155, -1, v155
	v_mul_u32_u24_e32 v155, 0x3000, v155
	v_add_u32_e32 v155, v155, v176
	global_load_dwordx2 v[70:71], v155, s[48:49]
	v_add_u32_e32 v156, 0x1000, v155
	global_load_dwordx2 v[72:73], v156, s[48:49]
	v_add_u32_e32 v157, 0x2000, v155
	global_load_dwordx2 v[74:75], v157, s[48:49]
	global_load_dwordx2 v[76:77], v154, s[48:49]
	v_add_u32_e32 v158, 0x1000, v154
	global_load_dwordx2 v[78:79], v158, s[48:49]
	v_add_u32_e32 v159, 0x2000, v154
	global_load_dwordx2 v[80:81], v159, s[48:49]
	v_add_u32_e32 v160, 0x3000, v154
	global_load_dwordx2 v[82:83], v160, s[48:49]
	v_add_u32_e32 v161, 0x4000, v154
	global_load_dwordx2 v[84:85], v161, s[48:49]
	v_add_u32_e32 v162, 0x5000, v154
	global_load_dwordx2 v[86:87], v162, s[48:49]
	v_add_u32_e32 v163, 0x5d000, v154
	global_load_dwordx2 v[88:89], v163, s[48:49]
	v_add_u32_e32 v164, 0x5e000, v154
	global_load_dwordx2 v[90:91], v164, s[48:49]
	v_add_u32_e32 v165, 0x5f000, v154
	global_load_dwordx2 v[92:93], v165, s[48:49]
	v_add_u32_e32 v166, 0x60000, v154
	global_load_dwordx2 v[94:95], v166, s[48:49]
	v_add_u32_e32 v167, 0x61000, v154
	global_load_dwordx2 v[96:97], v167, s[48:49]
	v_add_u32_e32 v168, 0x62000, v154
	global_load_dwordx2 v[98:99], v168, s[48:49]
	v_add_u32_e32 v169, 0x63000, v154
	global_load_dwordx2 v[100:101], v169, s[48:49]
	v_add_u32_e32 v170, 0x64000, v154
	global_load_dwordx2 v[102:103], v170, s[48:49]
	v_add_u32_e32 v171, 0x65000, v154
	global_load_dwordx2 v[104:105], v171, s[48:49]
	v_add_u32_e32 v172, 0x2000, v177
	v_add_u32_e32 v173, 0x4000, v177
	global_load_dwordx4 v[118:121], v177, s[12:13]
	global_load_dwordx4 v[122:125], v172, s[12:13]
	global_load_dwordx4 v[126:129], v173, s[12:13]
	global_load_dwordx4 v[142:145], v177, s[10:11]
	global_load_dwordx4 v[146:149], v172, s[10:11]
	global_load_dwordx4 v[150:153], v173, s[10:11]
	global_load_dwordx4 v[130:133], v177, s[14:15]
	global_load_dwordx4 v[134:137], v172, s[14:15]
	global_load_dwordx4 v[138:141], v173, s[14:15]
	global_load_dwordx4 v[106:109], v177, s[8:9]
	global_load_dwordx4 v[110:113], v172, s[8:9]
	global_load_dwordx4 v[114:117], v173, s[8:9]
	v_mul_f32_e32 v0, v16, v26
	ds_write2_b32 v59, v22, v23 offset0:32 offset1:97
	v_mul_f32_e32 v1, v17, v27
	v_add_u32_e32 v22, s17, v55
	ds_write2_b32 v42, v0, v1 offset0:96 offset1:161
	v_mul_f32_e32 v0, v12, v10
	v_mul_f32_e32 v1, v13, v11
	v_ashrrev_i32_e32 v23, 31, v22
	ds_write2_b32 v59, v20, v21 offset0:162 offset1:227
	ds_write2_b32 v43, v0, v1 offset0:98 offset1:163
	s_waitcnt lgkmcnt(0)
	s_barrier
	ds_read2_b32 v[0:1], v56 offset1:1
	ds_read2_b32 v[10:11], v56 offset0:4 offset1:5
	ds_read2_b32 v[12:13], v56 offset0:6 offset1:7
	ds_read2_b32 v[2:3], v56 offset0:2 offset1:3
	v_lshlrev_b64 v[22:23], 13, v[22:23]
	s_ashr_i32 s17, s16, 31
	v_lshl_add_u64 v[22:23], v[22:23], 0, s[16:17]
	v_or_b32_e32 v22, v22, v4
	v_lshlrev_b64 v[22:23], 2, v[22:23]
	v_add_u32_e32 v6, 0x4100, v56
	v_add_u32_e32 v16, 0x4110, v56
	v_add_u32_e32 v17, 0x4108, v56
	v_add_u32_e32 v20, 0x4118, v56
	v_lshl_add_u64 v[24:25], s[46:47], 0, v[22:23]
	ds_read2_b32 v[14:15], v6 offset1:1
	ds_read2_b32 v[18:19], v16 offset1:1
	ds_read2_b32 v[16:17], v17 offset1:1
	ds_read2_b32 v[20:21], v20 offset1:1
	s_waitcnt lgkmcnt(4)
	global_store_dwordx4 v[24:25], v[0:3], off
	s_add_i32 s24, s24, s30
	s_add_i32 s4, s4, s5
	v_lshl_add_u64 v[0:1], s[26:27], 0, v[22:23]
	v_add_co_u32_e32 v2, vcc, s23, v0
	s_add_i32 s18, s18, s19
	s_nop 0
	v_addc_co_u32_e32 v3, vcc, 0, v1, vcc
	v_add_co_u32_e32 v0, vcc, 0x9200000, v0
	global_store_dwordx4 v[2:3], v[10:13], off offset:16
	v_lshl_add_u64 v[2:3], s[54:55], 0, v[22:23]
	v_addc_co_u32_e32 v1, vcc, 0, v1, vcc
	s_cmpk_gt_i32 s24, 0xfff
	s_waitcnt lgkmcnt(1)
	global_store_dwordx4 v[2:3], v[14:17], off
	s_waitcnt lgkmcnt(0)
	global_store_dwordx4 v[0:1], v[18:21], off offset:16
	s_barrier
	s_cbranch_scc1 .LBB0_1319
.LBB0_1295:
	s_and_b32 s16, s4, 0xffffffc0
	s_and_b32 s17, s18, 0x7c0
	v_add_u32_e32 v60, s16, v5
	v_or_b32_e32 v0, s17, v54
	v_mad_i64_i32 v[32:33], s[0:1], v60, s20, v[8:9]
	v_lshlrev_b32_e32 v10, 1, v0
	v_mov_b32_e32 v11, v7
	v_lshlrev_b32_e32 v6, 2, v0
	s_waitcnt vmcnt(0)
	v_lshl_add_u64 v[0:1], v[32:33], 0, v[10:11]
	v_mov_b64_e32 v[26:27], v[76:77]
	v_lshl_add_u64 v[20:21], s[12:13], 0, v[6:7]
	v_lshl_add_u64 v[24:25], s[10:11], 0, v[6:7]
	v_mov_b64_e32 v[12:13], v[118:119]
	v_mov_b64_e32 v[14:15], v[120:121]
	v_mov_b64_e32 v[16:17], v[142:143]
	v_mov_b64_e32 v[18:19], v[144:145]
	v_lshl_add_u64 v[22:23], s[14:15], 0, v[6:7]
	v_mov_b64_e32 v[0:1], v[130:131]
	v_mov_b64_e32 v[2:3], v[132:133]
	v_add_u32_e32 v28, -1, v60
	v_mad_u64_u32 v[42:43], s[0:1], v28, s20, v[8:9]
	v_cmp_lt_i32_e32 vcc, 0, v60
	s_waitcnt vmcnt(0)
	v_lshlrev_b32_e32 v28, 16, v26
	v_and_b32_e32 v29, 0xffff0000, v26
	v_lshlrev_b32_e32 v26, 16, v27
	v_and_b32_e32 v27, 0xffff0000, v27
	s_waitcnt lgkmcnt(0)
	v_pk_fma_f32 v[38:39], v[14:15], v[26:27], v[18:19]
	v_pk_fma_f32 v[40:41], v[12:13], v[28:29], v[16:17]
	s_and_saveexec_b64 s[0:1], vcc
	s_cbranch_execz .LBB0_1297
	v_lshl_add_u64 v[12:13], v[42:43], 0, v[10:11]
	v_mov_b64_e32 v[16:17], v[70:71]
	v_lshl_add_u64 v[12:13], s[8:9], 0, v[6:7]
	v_mov_b64_e32 v[12:13], v[106:107]
	v_mov_b64_e32 v[14:15], v[108:109]
	s_waitcnt vmcnt(0)
	v_lshlrev_b32_e32 v18, 16, v16
	v_and_b32_e32 v19, 0xffff0000, v16
	v_lshlrev_b32_e32 v16, 16, v17
	v_and_b32_e32 v17, 0xffff0000, v17
	s_waitcnt lgkmcnt(0)
	v_pk_fma_f32 v[38:39], v[14:15], v[16:17], v[38:39]
	v_pk_fma_f32 v[40:41], v[12:13], v[18:19], v[40:41]
